# branch-mix epilogue rewritten with gate and partial-sum loads two rows ahead; projection and branch output stores stay in flight into the next K loop
# speedup vs baseline: 1.0468x; 1.0020x over previous
; #define PG8_BAR __builtin_amdgcn_s_barrier()
; template <bool PERM>
; __device__ __forceinline__ void gemm_phase(LAS unsigned char* lds, const Gemm g, const Sched& S, const EpiDesc& E, const Ctx& C) {
;     ...
;         if (!has_next) break;
; #pragma unroll
;         for (int a = 0; a < 2; ++a)
; #pragma unroll
;             for (int b = 0; b < 2; ++b)
; #pragma unroll
;                 for (int m = 0; m < 4; ++m)
; #pragma unroll
;                     for (int n = 0; n < 2; ++n) acc[a][b][m][n] = (f32x4){0.f, 0.f, 0.f, 0.f};
;         cur = nxt; cA = nA; cB = nB; ++ui;
;         if (wr == 1) PG8_BAR;
.LBB0_61:
	s_add_i32 s22, s29, -2
	s_add_u32 s2, s2, 0x80
	s_addc_u32 s3, s3, 0
	s_add_u32 s23, s20, 0x100
	s_addc_u32 s36, s21, 0
	s_mov_b32 s20, 0
	s_mov_b64 s[46:47], 0x80
	s_cmp_ge_u32 s24, 2
	s_cbranch_scc1 .Lka_w16
	s_waitcnt vmcnt(0)
	s_branch .Lka_wd
.Lka_w16:
	s_waitcnt vmcnt(48)

; __device__ __forceinline__ f32x4 unpk4(u32x2 p) { f32x4 r; r[0] = __uint_as_float(p.x << 16); r[1] = __uint_as_float(p.x & 0xffff0000u); r[2] = __uint_as_float(p.y << 16); r[3] = __uint_as_float(p.y & 0xffff0000u); return r; }
; __device__ __forceinline__ u32x4 pk8(f32x4 a, f32x4 b) { const u32x2 p = pk4(a), q = pk4(b); return (u32x4){p.x, p.y, q.x, q.y}; }
; template <int K>
; __device__ __forceinline__ void epilogue_p(const f32x4 (&acc)[2][2][4][2], const Unit& u, const EpiDesc& E, const Ctx& C, int wr, int wc, int fr, int fq) {
;     ...
;     } else {
;         const int seg = u.seg;
; #pragma unroll
;         for (int ai = 0; ai < 2; ++ai)
; #pragma unroll
;         for (int mh = 0; mh < 2; ++mh) {
;             u32x4 gq[2][2], mf[2][2];
; #pragma unroll
;             for (int m2 = 0; m2 < 2; ++m2)
; #pragma unroll
;                 for (int bj = 0; bj < 2; ++bj) {
;                     const int row = row0 + 128 * ai + 16 * (2 * mh + m2), col = 256 * u.pn + 128 * bj + lc8;
;                     gq[m2][bj] = *(const u32x4*)(C.G + (size_t)row * 3072 + seg * 1024 + col);
;                     if (seg > 0) mf[m2][bj] = *(const u32x4*)(C.MIXB + (size_t)row * DM + col); else mf[m2][bj] = (u32x4){0u, 0u, 0u, 0u};
;                 }
; #pragma unroll
;             for (int m2 = 0; m2 < 2; ++m2)
; #pragma unroll
;                 for (int bj = 0; bj < 2; ++bj) {
;                     const int m = 2 * mh + m2;
;                     const int row = row0 + 128 * ai + 16 * m, col = 256 * u.pn + 128 * bj + lc8;
;                     const f32x4 r0 = acc[ai][bj][m][0] * unpk4((u32x2){gq[m2][bj].x, gq[m2][bj].y}) + unpk4((u32x2){mf[m2][bj].x, mf[m2][bj].y});
;                     const f32x4 r1 = acc[ai][bj][m][1] * unpk4((u32x2){gq[m2][bj].z, gq[m2][bj].w}) + unpk4((u32x2){mf[m2][bj].z, mf[m2][bj].w});
;                     *(u32x4*)(C.MIXB + (size_t)row * DM + col) = pk8(r0, r1);
;                 }
;         }
.LBB0_70:
	s_lshl_b32 s2, s28, 11
	v_readlane_b32 s22, v254, 31
	v_readlane_b32 s23, v254, 32
	v_lshl_add_u32 v196, s18, 8, v179
	v_lshl_or_b32 v197, s87, 8, v178
	v_mul_u32_u24_e32 v0, 0x1800, v196
	v_lshlrev_b32_e32 v192, 11, v196
	v_lshl_add_u32 v0, v197, 1, v0
	v_lshl_add_u32 v192, v197, 1, v192
	v_mov_b32_e32 v193, v192
	s_add_u32 s22, s22, s2
	s_addc_u32 s23, s23, 0
	s_cmp_gt_i32 s28, 0
	s_waitcnt lgkmcnt(0)
	s_cbranch_scc0 .Lbr_seg0
	global_load_dwordx4 v[130:133], v0, s[22:23]
	global_load_dwordx4 v[134:137], v0, s[22:23] offset:256
	global_load_dwordx4 v[138:141], v192, s[88:89]
	global_load_dwordx4 v[142:145], v192, s[88:89] offset:256
	v_add_u32_e32 v0, 0x18000, v0
	v_add_u32_e32 v192, 0x8000, v192
	global_load_dwordx4 v[146:149], v0, s[22:23]
	global_load_dwordx4 v[150:153], v0, s[22:23] offset:256
	global_load_dwordx4 v[154:157], v192, s[88:89]
	global_load_dwordx4 v[158:161], v192, s[88:89] offset:256
	v_add_u32_e32 v0, 0x18000, v0
	v_add_u32_e32 v192, 0x8000, v192
	s_waitcnt vmcnt(4)
	v_lshlrev_b32_e32 v184, 16, v130
	v_lshlrev_b32_e32 v185, 16, v131
	v_lshlrev_b32_e32 v186, 16, v132
	v_lshlrev_b32_e32 v187, 16, v133
	v_and_b32_e32 v130, 0xffff0000, v130
	v_and_b32_e32 v131, 0xffff0000, v131
	v_and_b32_e32 v132, 0xffff0000, v132
	v_and_b32_e32 v133, 0xffff0000, v133
	v_lshlrev_b32_e32 v188, 16, v138
	v_lshlrev_b32_e32 v189, 16, v139
	v_lshlrev_b32_e32 v190, 16, v140
	v_lshlrev_b32_e32 v191, 16, v141
	v_and_b32_e32 v138, 0xffff0000, v138
	v_and_b32_e32 v139, 0xffff0000, v139
	v_and_b32_e32 v140, 0xffff0000, v140
	v_and_b32_e32 v141, 0xffff0000, v141
	v_fma_f32 v126, v126, v184, v188
	v_fma_f32 v127, v127, v130, v138
	v_fma_f32 v128, v128, v185, v189
	v_fma_f32 v129, v129, v131, v139
	v_fma_f32 v122, v122, v186, v190
	v_fma_f32 v123, v123, v132, v140
	v_fma_f32 v124, v124, v187, v191
	v_fma_f32 v125, v125, v133, v141
	v_cvt_pk_bf16_f32 v138, v126, v127
	v_cvt_pk_bf16_f32 v139, v128, v129
	v_cvt_pk_bf16_f32 v140, v122, v123
	v_cvt_pk_bf16_f32 v141, v124, v125
	v_lshlrev_b32_e32 v184, 16, v134
	v_lshlrev_b32_e32 v185, 16, v135
	v_lshlrev_b32_e32 v186, 16, v136
	v_lshlrev_b32_e32 v187, 16, v137
	v_and_b32_e32 v134, 0xffff0000, v134
	v_and_b32_e32 v135, 0xffff0000, v135
	v_and_b32_e32 v136, 0xffff0000, v136
	v_and_b32_e32 v137, 0xffff0000, v137
	v_lshlrev_b32_e32 v188, 16, v142
	v_lshlrev_b32_e32 v189, 16, v143
	v_lshlrev_b32_e32 v190, 16, v144
	v_lshlrev_b32_e32 v191, 16, v145
	v_and_b32_e32 v142, 0xffff0000, v142
	v_and_b32_e32 v143, 0xffff0000, v143
	v_and_b32_e32 v144, 0xffff0000, v144
	v_and_b32_e32 v145, 0xffff0000, v145
	v_fma_f32 v118, v118, v184, v188
	v_fma_f32 v119, v119, v134, v142
	v_fma_f32 v120, v120, v185, v189
	v_fma_f32 v121, v121, v135, v143
	v_fma_f32 v114, v114, v186, v190
	v_fma_f32 v115, v115, v136, v144
	v_fma_f32 v116, v116, v187, v191
	v_fma_f32 v117, v117, v137, v145
	v_cvt_pk_bf16_f32 v142, v118, v119
	v_cvt_pk_bf16_f32 v143, v120, v121
	v_cvt_pk_bf16_f32 v144, v114, v115
	v_cvt_pk_bf16_f32 v145, v116, v117
	global_store_dwordx4 v193, v[138:141], s[88:89]
	global_store_dwordx4 v193, v[142:145], s[88:89] offset:256
	v_add_u32_e32 v193, 0x8000, v193
	global_load_dwordx4 v[162:165], v0, s[22:23]
	global_load_dwordx4 v[126:129], v0, s[22:23] offset:256
	global_load_dwordx4 v[122:125], v192, s[88:89]
	global_load_dwordx4 v[118:121], v192, s[88:89] offset:256
	v_add_u32_e32 v0, 0x18000, v0
	v_add_u32_e32 v192, 0x8000, v192
	s_waitcnt vmcnt(6)
	v_lshlrev_b32_e32 v184, 16, v146
	v_lshlrev_b32_e32 v185, 16, v147
	v_lshlrev_b32_e32 v186, 16, v148
	v_lshlrev_b32_e32 v187, 16, v149
	v_and_b32_e32 v146, 0xffff0000, v146
	v_and_b32_e32 v147, 0xffff0000, v147
	v_and_b32_e32 v148, 0xffff0000, v148
	v_and_b32_e32 v149, 0xffff0000, v149
	v_lshlrev_b32_e32 v188, 16, v154
	v_lshlrev_b32_e32 v189, 16, v155
	v_lshlrev_b32_e32 v190, 16, v156
	v_lshlrev_b32_e32 v191, 16, v157
	v_and_b32_e32 v154, 0xffff0000, v154
	v_and_b32_e32 v155, 0xffff0000, v155
	v_and_b32_e32 v156, 0xffff0000, v156
	v_and_b32_e32 v157, 0xffff0000, v157
	v_fma_f32 v110, v110, v184, v188
	v_fma_f32 v111, v111, v146, v154
	v_fma_f32 v112, v112, v185, v189
	v_fma_f32 v113, v113, v147, v155
	v_fma_f32 v106, v106, v186, v190
	v_fma_f32 v107, v107, v148, v156
	v_fma_f32 v108, v108, v187, v191
	v_fma_f32 v109, v109, v149, v157
	v_cvt_pk_bf16_f32 v154, v110, v111
	v_cvt_pk_bf16_f32 v155, v112, v113
	v_cvt_pk_bf16_f32 v156, v106, v107
	v_cvt_pk_bf16_f32 v157, v108, v109
	v_lshlrev_b32_e32 v184, 16, v150
	v_lshlrev_b32_e32 v185, 16, v151
	v_lshlrev_b32_e32 v186, 16, v152
	v_lshlrev_b32_e32 v187, 16, v153
	v_and_b32_e32 v150, 0xffff0000, v150
	v_and_b32_e32 v151, 0xffff0000, v151
	v_and_b32_e32 v152, 0xffff0000, v152
	v_and_b32_e32 v153, 0xffff0000, v153
	v_lshlrev_b32_e32 v188, 16, v158
	v_lshlrev_b32_e32 v189, 16, v159
	v_lshlrev_b32_e32 v190, 16, v160
	v_lshlrev_b32_e32 v191, 16, v161
	v_and_b32_e32 v158, 0xffff0000, v158
	v_and_b32_e32 v159, 0xffff0000, v159
	v_and_b32_e32 v160, 0xffff0000, v160
	v_and_b32_e32 v161, 0xffff0000, v161
	v_fma_f32 v102, v102, v184, v188
	v_fma_f32 v103, v103, v150, v158
	v_fma_f32 v104, v104, v185, v189
	v_fma_f32 v105, v105, v151, v159
	v_fma_f32 v98, v98, v186, v190
	v_fma_f32 v99, v99, v152, v160
	v_fma_f32 v100, v100, v187, v191
	v_fma_f32 v101, v101, v153, v161
	v_cvt_pk_bf16_f32 v158, v102, v103
	v_cvt_pk_bf16_f32 v159, v104, v105
	v_cvt_pk_bf16_f32 v160, v98, v99
	v_cvt_pk_bf16_f32 v161, v100, v101
	global_store_dwordx4 v193, v[154:157], s[88:89]
	global_store_dwordx4 v193, v[158:161], s[88:89] offset:256
	v_add_u32_e32 v193, 0x8000, v193
	global_load_dwordx4 v[114:117], v0, s[22:23]
	global_load_dwordx4 v[130:133], v0, s[22:23] offset:256
	global_load_dwordx4 v[134:137], v192, s[88:89]
	global_load_dwordx4 v[110:113], v192, s[88:89] offset:256
	v_add_u32_e32 v0, 0x78000, v0
	v_add_u32_e32 v192, 0x28000, v192
	global_load_dwordx4 v[106:109], v0, s[22:23]
	global_load_dwordx4 v[102:105], v0, s[22:23] offset:256
	global_load_dwordx4 v[98:101], v192, s[88:89]
	global_load_dwordx4 v[146:149], v192, s[88:89] offset:256
	v_add_u32_e32 v0, 0x18000, v0
	v_add_u32_e32 v192, 0x8000, v192
	s_waitcnt vmcnt(10)
; __device__ __forceinline__ f32x4 unpk4(u32x2 p) { f32x4 r; r[0] = __uint_as_float(p.x << 16); r[1] = __uint_as_float(p.x & 0xffff0000u); r[2] = __uint_as_float(p.y << 16); r[3] = __uint_as_float(p.y & 0xffff0000u); return r; }
; __device__ __forceinline__ u32x4 pk8(f32x4 a, f32x4 b) { const u32x2 p = pk4(a), q = pk4(b); return (u32x4){p.x, p.y, q.x, q.y}; }
; template <int K>
; __device__ __forceinline__ void epilogue_p(const f32x4 (&acc)[2][2][4][2], const Unit& u, const EpiDesc& E, const Ctx& C, int wr, int wc, int fr, int fq) {
;     ...
;             for (int m2 = 0; m2 < 2; ++m2)
; #pragma unroll
;                 for (int bj = 0; bj < 2; ++bj) {
;                     const int m = 2 * mh + m2;
;                     const int row = row0 + 128 * ai + 16 * m, col = 256 * u.pn + 128 * bj + lc8;
;                     const f32x4 r0 = acc[ai][bj][m][0] * unpk4((u32x2){gq[m2][bj].x, gq[m2][bj].y}) + unpk4((u32x2){mf[m2][bj].x, mf[m2][bj].y});
;                     const f32x4 r1 = acc[ai][bj][m][1] * unpk4((u32x2){gq[m2][bj].z, gq[m2][bj].w}) + unpk4((u32x2){mf[m2][bj].z, mf[m2][bj].w});
;                     *(u32x4*)(C.MIXB + (size_t)row * DM + col) = pk8(r0, r1);
;                 }
	v_lshlrev_b32_e32 v184, 16, v162
	v_lshlrev_b32_e32 v185, 16, v163
	v_lshlrev_b32_e32 v186, 16, v164
	v_lshlrev_b32_e32 v187, 16, v165
	v_and_b32_e32 v162, 0xffff0000, v162
	v_and_b32_e32 v163, 0xffff0000, v163
	v_and_b32_e32 v164, 0xffff0000, v164
	v_and_b32_e32 v165, 0xffff0000, v165
	v_lshlrev_b32_e32 v188, 16, v122
	v_lshlrev_b32_e32 v189, 16, v123
	v_lshlrev_b32_e32 v190, 16, v124
	v_lshlrev_b32_e32 v191, 16, v125
	v_and_b32_e32 v122, 0xffff0000, v122
	v_and_b32_e32 v123, 0xffff0000, v123
	v_and_b32_e32 v124, 0xffff0000, v124
	v_and_b32_e32 v125, 0xffff0000, v125
	v_fma_f32 v94, v94, v184, v188
	v_fma_f32 v95, v95, v162, v122
	v_fma_f32 v96, v96, v185, v189
	v_fma_f32 v97, v97, v163, v123
	v_fma_f32 v90, v90, v186, v190
	v_fma_f32 v91, v91, v164, v124
	v_fma_f32 v92, v92, v187, v191
	v_fma_f32 v93, v93, v165, v125
	v_cvt_pk_bf16_f32 v122, v94, v95
	v_cvt_pk_bf16_f32 v123, v96, v97
	v_cvt_pk_bf16_f32 v124, v90, v91
	v_cvt_pk_bf16_f32 v125, v92, v93
	v_lshlrev_b32_e32 v184, 16, v126
	v_lshlrev_b32_e32 v185, 16, v127
	v_lshlrev_b32_e32 v186, 16, v128
	v_lshlrev_b32_e32 v187, 16, v129
	v_and_b32_e32 v126, 0xffff0000, v126
	v_and_b32_e32 v127, 0xffff0000, v127
	v_and_b32_e32 v128, 0xffff0000, v128
	v_and_b32_e32 v129, 0xffff0000, v129
	v_lshlrev_b32_e32 v188, 16, v118
	v_lshlrev_b32_e32 v189, 16, v119
	v_lshlrev_b32_e32 v190, 16, v120
	v_lshlrev_b32_e32 v191, 16, v121
	v_and_b32_e32 v118, 0xffff0000, v118
	v_and_b32_e32 v119, 0xffff0000, v119
	v_and_b32_e32 v120, 0xffff0000, v120
	v_and_b32_e32 v121, 0xffff0000, v121
	v_fma_f32 v86, v86, v184, v188
	v_fma_f32 v87, v87, v126, v118
	v_fma_f32 v88, v88, v185, v189
	v_fma_f32 v89, v89, v127, v119
	v_fma_f32 v82, v82, v186, v190
	v_fma_f32 v83, v83, v128, v120
	v_fma_f32 v84, v84, v187, v191
	v_fma_f32 v85, v85, v129, v121
	v_cvt_pk_bf16_f32 v118, v86, v87
	v_cvt_pk_bf16_f32 v119, v88, v89
	v_cvt_pk_bf16_f32 v120, v82, v83
	v_cvt_pk_bf16_f32 v121, v84, v85
	global_store_dwordx4 v193, v[122:125], s[88:89]
	global_store_dwordx4 v193, v[118:121], s[88:89] offset:256
	v_add_u32_e32 v193, 0x8000, v193
	global_load_dwordx4 v[150:153], v0, s[22:23]
	global_load_dwordx4 v[94:97], v0, s[22:23] offset:256
	global_load_dwordx4 v[90:93], v192, s[88:89]
	global_load_dwordx4 v[86:89], v192, s[88:89] offset:256
	v_add_u32_e32 v0, 0x18000, v0
	v_add_u32_e32 v192, 0x8000, v192
	s_waitcnt vmcnt(10)
	v_lshlrev_b32_e32 v184, 16, v114
	v_lshlrev_b32_e32 v185, 16, v115
	v_lshlrev_b32_e32 v186, 16, v116
	v_lshlrev_b32_e32 v187, 16, v117
	v_and_b32_e32 v114, 0xffff0000, v114
	v_and_b32_e32 v115, 0xffff0000, v115
	v_and_b32_e32 v116, 0xffff0000, v116
	v_and_b32_e32 v117, 0xffff0000, v117
	v_lshlrev_b32_e32 v188, 16, v134
	v_lshlrev_b32_e32 v189, 16, v135
	v_lshlrev_b32_e32 v190, 16, v136
	v_lshlrev_b32_e32 v191, 16, v137
	v_and_b32_e32 v134, 0xffff0000, v134
	v_and_b32_e32 v135, 0xffff0000, v135
	v_and_b32_e32 v136, 0xffff0000, v136
	v_and_b32_e32 v137, 0xffff0000, v137
	v_fma_f32 v78, v78, v184, v188
	v_fma_f32 v79, v79, v114, v134
	v_fma_f32 v80, v80, v185, v189
	v_fma_f32 v81, v81, v115, v135
	v_fma_f32 v74, v74, v186, v190
	v_fma_f32 v75, v75, v116, v136
	v_fma_f32 v76, v76, v187, v191
	v_fma_f32 v77, v77, v117, v137
	v_cvt_pk_bf16_f32 v134, v78, v79
	v_cvt_pk_bf16_f32 v135, v80, v81
	v_cvt_pk_bf16_f32 v136, v74, v75
	v_cvt_pk_bf16_f32 v137, v76, v77
	v_lshlrev_b32_e32 v184, 16, v130
	v_lshlrev_b32_e32 v185, 16, v131
	v_lshlrev_b32_e32 v186, 16, v132
	v_lshlrev_b32_e32 v187, 16, v133
	v_and_b32_e32 v130, 0xffff0000, v130
	v_and_b32_e32 v131, 0xffff0000, v131
	v_and_b32_e32 v132, 0xffff0000, v132
	v_and_b32_e32 v133, 0xffff0000, v133
	v_lshlrev_b32_e32 v188, 16, v110
	v_lshlrev_b32_e32 v189, 16, v111
	v_lshlrev_b32_e32 v190, 16, v112
	v_lshlrev_b32_e32 v191, 16, v113
	v_and_b32_e32 v110, 0xffff0000, v110
	v_and_b32_e32 v111, 0xffff0000, v111
	v_and_b32_e32 v112, 0xffff0000, v112
	v_and_b32_e32 v113, 0xffff0000, v113
	v_fma_f32 v70, v70, v184, v188
	v_fma_f32 v71, v71, v130, v110
	v_fma_f32 v72, v72, v185, v189
	v_fma_f32 v73, v73, v131, v111
	v_fma_f32 v66, v66, v186, v190
	v_fma_f32 v67, v67, v132, v112
	v_fma_f32 v68, v68, v187, v191
	v_fma_f32 v69, v69, v133, v113
	v_cvt_pk_bf16_f32 v110, v70, v71
	v_cvt_pk_bf16_f32 v111, v72, v73
	v_cvt_pk_bf16_f32 v112, v66, v67
	v_cvt_pk_bf16_f32 v113, v68, v69
	global_store_dwordx4 v193, v[134:137], s[88:89]
	global_store_dwordx4 v193, v[110:113], s[88:89] offset:256
	v_add_u32_e32 v193, 0x28000, v193
	global_load_dwordx4 v[82:85], v0, s[22:23]
	global_load_dwordx4 v[162:165], v0, s[22:23] offset:256
	global_load_dwordx4 v[126:129], v192, s[88:89]
	global_load_dwordx4 v[78:81], v192, s[88:89] offset:256
	v_add_u32_e32 v0, 0x18000, v0
	v_add_u32_e32 v192, 0x8000, v192
	s_waitcnt vmcnt(12)
; __device__ __forceinline__ f32x4 unpk4(u32x2 p) { f32x4 r; r[0] = __uint_as_float(p.x << 16); r[1] = __uint_as_float(p.x & 0xffff0000u); r[2] = __uint_as_float(p.y << 16); r[3] = __uint_as_float(p.y & 0xffff0000u); return r; }
; __device__ __forceinline__ u32x4 pk8(f32x4 a, f32x4 b) { const u32x2 p = pk4(a), q = pk4(b); return (u32x4){p.x, p.y, q.x, q.y}; }
; template <int K>
; __device__ __forceinline__ void epilogue_p(const f32x4 (&acc)[2][2][4][2], const Unit& u, const EpiDesc& E, const Ctx& C, int wr, int wc, int fr, int fq) {
;     ...
;             for (int m2 = 0; m2 < 2; ++m2)
; #pragma unroll
;                 for (int bj = 0; bj < 2; ++bj) {
;                     const int m = 2 * mh + m2;
;                     const int row = row0 + 128 * ai + 16 * m, col = 256 * u.pn + 128 * bj + lc8;
;                     const f32x4 r0 = acc[ai][bj][m][0] * unpk4((u32x2){gq[m2][bj].x, gq[m2][bj].y}) + unpk4((u32x2){mf[m2][bj].x, mf[m2][bj].y});
;                     const f32x4 r1 = acc[ai][bj][m][1] * unpk4((u32x2){gq[m2][bj].z, gq[m2][bj].w}) + unpk4((u32x2){mf[m2][bj].z, mf[m2][bj].w});
;                     *(u32x4*)(C.MIXB + (size_t)row * DM + col) = pk8(r0, r1);
;                 }
	v_lshlrev_b32_e32 v184, 16, v106
	v_lshlrev_b32_e32 v185, 16, v107
	v_lshlrev_b32_e32 v186, 16, v108
	v_lshlrev_b32_e32 v187, 16, v109
	v_and_b32_e32 v106, 0xffff0000, v106
	v_and_b32_e32 v107, 0xffff0000, v107
	v_and_b32_e32 v108, 0xffff0000, v108
	v_and_b32_e32 v109, 0xffff0000, v109
	v_lshlrev_b32_e32 v188, 16, v98
	v_lshlrev_b32_e32 v189, 16, v99
	v_lshlrev_b32_e32 v190, 16, v100
	v_lshlrev_b32_e32 v191, 16, v101
	v_and_b32_e32 v98, 0xffff0000, v98
	v_and_b32_e32 v99, 0xffff0000, v99
	v_and_b32_e32 v100, 0xffff0000, v100
	v_and_b32_e32 v101, 0xffff0000, v101
	v_fma_f32 v62, v62, v184, v188
	v_fma_f32 v63, v63, v106, v98
	v_fma_f32 v64, v64, v185, v189
	v_fma_f32 v65, v65, v107, v99
	v_fma_f32 v58, v58, v186, v190
	v_fma_f32 v59, v59, v108, v100
	v_fma_f32 v60, v60, v187, v191
	v_fma_f32 v61, v61, v109, v101
	v_cvt_pk_bf16_f32 v98, v62, v63
	v_cvt_pk_bf16_f32 v99, v64, v65
	v_cvt_pk_bf16_f32 v100, v58, v59
	v_cvt_pk_bf16_f32 v101, v60, v61
	v_lshlrev_b32_e32 v184, 16, v102
	v_lshlrev_b32_e32 v185, 16, v103
	v_lshlrev_b32_e32 v186, 16, v104
	v_lshlrev_b32_e32 v187, 16, v105
	v_and_b32_e32 v102, 0xffff0000, v102
	v_and_b32_e32 v103, 0xffff0000, v103
	v_and_b32_e32 v104, 0xffff0000, v104
	v_and_b32_e32 v105, 0xffff0000, v105
	v_lshlrev_b32_e32 v188, 16, v146
	v_lshlrev_b32_e32 v189, 16, v147
	v_lshlrev_b32_e32 v190, 16, v148
	v_lshlrev_b32_e32 v191, 16, v149
	v_and_b32_e32 v146, 0xffff0000, v146
	v_and_b32_e32 v147, 0xffff0000, v147
	v_and_b32_e32 v148, 0xffff0000, v148
	v_and_b32_e32 v149, 0xffff0000, v149
	v_fma_f32 v54, v54, v184, v188
	v_fma_f32 v55, v55, v102, v146
	v_fma_f32 v56, v56, v185, v189
	v_fma_f32 v57, v57, v103, v147
	v_fma_f32 v50, v50, v186, v190
	v_fma_f32 v51, v51, v104, v148
	v_fma_f32 v52, v52, v187, v191
	v_fma_f32 v53, v53, v105, v149
	v_cvt_pk_bf16_f32 v146, v54, v55
	v_cvt_pk_bf16_f32 v147, v56, v57
	v_cvt_pk_bf16_f32 v148, v50, v51
	v_cvt_pk_bf16_f32 v149, v52, v53
	global_store_dwordx4 v193, v[98:101], s[88:89]
	global_store_dwordx4 v193, v[146:149], s[88:89] offset:256
	v_add_u32_e32 v193, 0x8000, v193
	global_load_dwordx4 v[74:77], v0, s[22:23]
	global_load_dwordx4 v[70:73], v0, s[22:23] offset:256
	global_load_dwordx4 v[66:69], v192, s[88:89]
	global_load_dwordx4 v[114:117], v192, s[88:89] offset:256
	s_waitcnt vmcnt(12)
	v_lshlrev_b32_e32 v184, 16, v150
	v_lshlrev_b32_e32 v185, 16, v151
	v_lshlrev_b32_e32 v186, 16, v152
	v_lshlrev_b32_e32 v187, 16, v153
	v_and_b32_e32 v150, 0xffff0000, v150
	v_and_b32_e32 v151, 0xffff0000, v151
	v_and_b32_e32 v152, 0xffff0000, v152
	v_and_b32_e32 v153, 0xffff0000, v153
	v_lshlrev_b32_e32 v188, 16, v90
	v_lshlrev_b32_e32 v189, 16, v91
	v_lshlrev_b32_e32 v190, 16, v92
	v_lshlrev_b32_e32 v191, 16, v93
	v_and_b32_e32 v90, 0xffff0000, v90
	v_and_b32_e32 v91, 0xffff0000, v91
	v_and_b32_e32 v92, 0xffff0000, v92
	v_and_b32_e32 v93, 0xffff0000, v93
	v_fma_f32 v46, v46, v184, v188
	v_fma_f32 v47, v47, v150, v90
	v_fma_f32 v48, v48, v185, v189
	v_fma_f32 v49, v49, v151, v91
	v_fma_f32 v42, v42, v186, v190
	v_fma_f32 v43, v43, v152, v92
	v_fma_f32 v44, v44, v187, v191
	v_fma_f32 v45, v45, v153, v93
	v_cvt_pk_bf16_f32 v90, v46, v47
	v_cvt_pk_bf16_f32 v91, v48, v49
	v_cvt_pk_bf16_f32 v92, v42, v43
	v_cvt_pk_bf16_f32 v93, v44, v45
	v_lshlrev_b32_e32 v184, 16, v94
	v_lshlrev_b32_e32 v185, 16, v95
	v_lshlrev_b32_e32 v186, 16, v96
	v_lshlrev_b32_e32 v187, 16, v97
	v_and_b32_e32 v94, 0xffff0000, v94
	v_and_b32_e32 v95, 0xffff0000, v95
	v_and_b32_e32 v96, 0xffff0000, v96
	v_and_b32_e32 v97, 0xffff0000, v97
	v_lshlrev_b32_e32 v188, 16, v86
	v_lshlrev_b32_e32 v189, 16, v87
	v_lshlrev_b32_e32 v190, 16, v88
	v_lshlrev_b32_e32 v191, 16, v89
	v_and_b32_e32 v86, 0xffff0000, v86
	v_and_b32_e32 v87, 0xffff0000, v87
	v_and_b32_e32 v88, 0xffff0000, v88
	v_and_b32_e32 v89, 0xffff0000, v89
	v_fma_f32 v38, v38, v184, v188
	v_fma_f32 v39, v39, v94, v86
	v_fma_f32 v40, v40, v185, v189
	v_fma_f32 v41, v41, v95, v87
	v_fma_f32 v34, v34, v186, v190
	v_fma_f32 v35, v35, v96, v88
	v_fma_f32 v36, v36, v187, v191
	v_fma_f32 v37, v37, v97, v89
	v_cvt_pk_bf16_f32 v86, v38, v39
	v_cvt_pk_bf16_f32 v87, v40, v41
	v_cvt_pk_bf16_f32 v88, v34, v35
	v_cvt_pk_bf16_f32 v89, v36, v37
	global_store_dwordx4 v193, v[90:93], s[88:89]
	global_store_dwordx4 v193, v[86:89], s[88:89] offset:256
	v_add_u32_e32 v193, 0x8000, v193
	s_waitcnt vmcnt(8)
	v_lshlrev_b32_e32 v184, 16, v82
	v_lshlrev_b32_e32 v185, 16, v83
	v_lshlrev_b32_e32 v186, 16, v84
	v_lshlrev_b32_e32 v187, 16, v85
	v_and_b32_e32 v82, 0xffff0000, v82
	v_and_b32_e32 v83, 0xffff0000, v83
	v_and_b32_e32 v84, 0xffff0000, v84
	v_and_b32_e32 v85, 0xffff0000, v85
	v_lshlrev_b32_e32 v188, 16, v126
	v_lshlrev_b32_e32 v189, 16, v127
	v_lshlrev_b32_e32 v190, 16, v128
	v_lshlrev_b32_e32 v191, 16, v129
	v_and_b32_e32 v126, 0xffff0000, v126
	v_and_b32_e32 v127, 0xffff0000, v127
	v_and_b32_e32 v128, 0xffff0000, v128
	v_and_b32_e32 v129, 0xffff0000, v129
	v_fma_f32 v30, v30, v184, v188
	v_fma_f32 v31, v31, v82, v126
	v_fma_f32 v32, v32, v185, v189
	v_fma_f32 v33, v33, v83, v127
	v_fma_f32 v26, v26, v186, v190
	v_fma_f32 v27, v27, v84, v128
	v_fma_f32 v28, v28, v187, v191
	v_fma_f32 v29, v29, v85, v129
	v_cvt_pk_bf16_f32 v126, v30, v31
	v_cvt_pk_bf16_f32 v127, v32, v33
	v_cvt_pk_bf16_f32 v128, v26, v27
	v_cvt_pk_bf16_f32 v129, v28, v29
	v_lshlrev_b32_e32 v184, 16, v162
	v_lshlrev_b32_e32 v185, 16, v163
	v_lshlrev_b32_e32 v186, 16, v164
	v_lshlrev_b32_e32 v187, 16, v165
	v_and_b32_e32 v162, 0xffff0000, v162
	v_and_b32_e32 v163, 0xffff0000, v163
	v_and_b32_e32 v164, 0xffff0000, v164
	v_and_b32_e32 v165, 0xffff0000, v165
	v_lshlrev_b32_e32 v188, 16, v78
	v_lshlrev_b32_e32 v189, 16, v79
	v_lshlrev_b32_e32 v190, 16, v80
	v_lshlrev_b32_e32 v191, 16, v81
	v_and_b32_e32 v78, 0xffff0000, v78
	v_and_b32_e32 v79, 0xffff0000, v79
	v_and_b32_e32 v80, 0xffff0000, v80
	v_and_b32_e32 v81, 0xffff0000, v81
	v_fma_f32 v22, v22, v184, v188
	v_fma_f32 v23, v23, v162, v78
	v_fma_f32 v24, v24, v185, v189
	v_fma_f32 v25, v25, v163, v79
	v_fma_f32 v18, v18, v186, v190
	v_fma_f32 v19, v19, v164, v80
	v_fma_f32 v20, v20, v187, v191
	v_fma_f32 v21, v21, v165, v81
	v_cvt_pk_bf16_f32 v78, v22, v23
	v_cvt_pk_bf16_f32 v79, v24, v25
	v_cvt_pk_bf16_f32 v80, v18, v19
	v_cvt_pk_bf16_f32 v81, v20, v21
	global_store_dwordx4 v193, v[126:129], s[88:89]
	global_store_dwordx4 v193, v[78:81], s[88:89] offset:256
	v_add_u32_e32 v193, 0x8000, v193
	s_waitcnt vmcnt(4)
; __device__ __forceinline__ f32x4 unpk4(u32x2 p) { f32x4 r; r[0] = __uint_as_float(p.x << 16); r[1] = __uint_as_float(p.x & 0xffff0000u); r[2] = __uint_as_float(p.y << 16); r[3] = __uint_as_float(p.y & 0xffff0000u); return r; }
; __device__ __forceinline__ u32x4 pk8(f32x4 a, f32x4 b) { const u32x2 p = pk4(a), q = pk4(b); return (u32x4){p.x, p.y, q.x, q.y}; }
; template <int K>
; __device__ __forceinline__ void epilogue_p(const f32x4 (&acc)[2][2][4][2], const Unit& u, const EpiDesc& E, const Ctx& C, int wr, int wc, int fr, int fq) {
;     ...
;                     const int row = row0 + 128 * ai + 16 * (2 * mh + m2), col = 256 * u.pn + 128 * bj + lc8;
;                     gq[m2][bj] = *(const u32x4*)(C.G + (size_t)row * 3072 + seg * 1024 + col);
;                     if (seg > 0) mf[m2][bj] = *(const u32x4*)(C.MIXB + (size_t)row * DM + col); else mf[m2][bj] = (u32x4){0u, 0u, 0u, 0u};
;                 }
; #pragma unroll
;             for (int m2 = 0; m2 < 2; ++m2)
; #pragma unroll
;                 for (int bj = 0; bj < 2; ++bj) {
;                     const int m = 2 * mh + m2;
;                     const int row = row0 + 128 * ai + 16 * m, col = 256 * u.pn + 128 * bj + lc8;
;                     const f32x4 r0 = acc[ai][bj][m][0] * unpk4((u32x2){gq[m2][bj].x, gq[m2][bj].y}) + unpk4((u32x2){mf[m2][bj].x, mf[m2][bj].y});
;                     const f32x4 r1 = acc[ai][bj][m][1] * unpk4((u32x2){gq[m2][bj].z, gq[m2][bj].w}) + unpk4((u32x2){mf[m2][bj].z, mf[m2][bj].w});
;                     *(u32x4*)(C.MIXB + (size_t)row * DM + col) = pk8(r0, r1);
;                 }
	v_lshlrev_b32_e32 v184, 16, v74
	v_lshlrev_b32_e32 v185, 16, v75
	v_lshlrev_b32_e32 v186, 16, v76
	v_lshlrev_b32_e32 v187, 16, v77
	v_and_b32_e32 v74, 0xffff0000, v74
	v_and_b32_e32 v75, 0xffff0000, v75
	v_and_b32_e32 v76, 0xffff0000, v76
	v_and_b32_e32 v77, 0xffff0000, v77
	v_lshlrev_b32_e32 v188, 16, v66
	v_lshlrev_b32_e32 v189, 16, v67
	v_lshlrev_b32_e32 v190, 16, v68
	v_lshlrev_b32_e32 v191, 16, v69
	v_and_b32_e32 v66, 0xffff0000, v66
	v_and_b32_e32 v67, 0xffff0000, v67
	v_and_b32_e32 v68, 0xffff0000, v68
	v_and_b32_e32 v69, 0xffff0000, v69
	v_fma_f32 v14, v14, v184, v188
	v_fma_f32 v15, v15, v74, v66
	v_fma_f32 v16, v16, v185, v189
	v_fma_f32 v17, v17, v75, v67
	v_fma_f32 v10, v10, v186, v190
	v_fma_f32 v11, v11, v76, v68
	v_fma_f32 v12, v12, v187, v191
	v_fma_f32 v13, v13, v77, v69
	v_cvt_pk_bf16_f32 v66, v14, v15
	v_cvt_pk_bf16_f32 v67, v16, v17
	v_cvt_pk_bf16_f32 v68, v10, v11
	v_cvt_pk_bf16_f32 v69, v12, v13
	v_lshlrev_b32_e32 v184, 16, v70
	v_lshlrev_b32_e32 v185, 16, v71
	v_lshlrev_b32_e32 v186, 16, v72
	v_lshlrev_b32_e32 v187, 16, v73
	v_and_b32_e32 v70, 0xffff0000, v70
	v_and_b32_e32 v71, 0xffff0000, v71
	v_and_b32_e32 v72, 0xffff0000, v72
	v_and_b32_e32 v73, 0xffff0000, v73
	v_lshlrev_b32_e32 v188, 16, v114
	v_lshlrev_b32_e32 v189, 16, v115
	v_lshlrev_b32_e32 v190, 16, v116
	v_lshlrev_b32_e32 v191, 16, v117
	v_and_b32_e32 v114, 0xffff0000, v114
	v_and_b32_e32 v115, 0xffff0000, v115
	v_and_b32_e32 v116, 0xffff0000, v116
	v_and_b32_e32 v117, 0xffff0000, v117
	v_fma_f32 v6, v6, v184, v188
	v_fma_f32 v7, v7, v70, v114
	v_fma_f32 v8, v8, v185, v189
	v_fma_f32 v9, v9, v71, v115
	v_fma_f32 v2, v2, v186, v190
	v_fma_f32 v3, v3, v72, v116
	v_fma_f32 v4, v4, v187, v191
	v_fma_f32 v5, v5, v73, v117
	v_cvt_pk_bf16_f32 v114, v6, v7
	v_cvt_pk_bf16_f32 v115, v8, v9
	v_cvt_pk_bf16_f32 v116, v2, v3
	v_cvt_pk_bf16_f32 v117, v4, v5
	global_store_dwordx4 v193, v[66:69], s[88:89]
	global_store_dwordx4 v193, v[114:117], s[88:89] offset:256
	s_branch .LBB0_213
.Lbr_seg0:
	global_load_dwordx4 v[130:133], v0, s[22:23]
	global_load_dwordx4 v[134:137], v0, s[22:23] offset:256
	v_add_u32_e32 v0, 0x18000, v0
	global_load_dwordx4 v[138:141], v0, s[22:23]
	global_load_dwordx4 v[142:145], v0, s[22:23] offset:256
	v_add_u32_e32 v0, 0x18000, v0
	s_waitcnt vmcnt(2)
	v_lshlrev_b32_e32 v184, 16, v130
	v_lshlrev_b32_e32 v185, 16, v131
	v_lshlrev_b32_e32 v186, 16, v132
	v_lshlrev_b32_e32 v187, 16, v133
	v_and_b32_e32 v130, 0xffff0000, v130
	v_and_b32_e32 v131, 0xffff0000, v131
	v_and_b32_e32 v132, 0xffff0000, v132
	v_and_b32_e32 v133, 0xffff0000, v133
	v_mul_f32_e32 v126, v126, v184
	v_mul_f32_e32 v127, v127, v130
	v_mul_f32_e32 v128, v128, v185
	v_mul_f32_e32 v129, v129, v131
	v_mul_f32_e32 v122, v122, v186
	v_mul_f32_e32 v123, v123, v132
	v_mul_f32_e32 v124, v124, v187
	v_mul_f32_e32 v125, v125, v133
	v_cvt_pk_bf16_f32 v130, v126, v127
	v_cvt_pk_bf16_f32 v131, v128, v129
	v_cvt_pk_bf16_f32 v132, v122, v123
	v_cvt_pk_bf16_f32 v133, v124, v125
	v_lshlrev_b32_e32 v184, 16, v134
	v_lshlrev_b32_e32 v185, 16, v135
	v_lshlrev_b32_e32 v186, 16, v136
	v_lshlrev_b32_e32 v187, 16, v137
	v_and_b32_e32 v134, 0xffff0000, v134
	v_and_b32_e32 v135, 0xffff0000, v135
	v_and_b32_e32 v136, 0xffff0000, v136
	v_and_b32_e32 v137, 0xffff0000, v137
	v_mul_f32_e32 v118, v118, v184
	v_mul_f32_e32 v119, v119, v134
	v_mul_f32_e32 v120, v120, v185
	v_mul_f32_e32 v121, v121, v135
	v_mul_f32_e32 v114, v114, v186
	v_mul_f32_e32 v115, v115, v136
	v_mul_f32_e32 v116, v116, v187
	v_mul_f32_e32 v117, v117, v137
	v_cvt_pk_bf16_f32 v134, v118, v119
	v_cvt_pk_bf16_f32 v135, v120, v121
	v_cvt_pk_bf16_f32 v136, v114, v115
	v_cvt_pk_bf16_f32 v137, v116, v117
	global_store_dwordx4 v193, v[130:133], s[88:89]
	global_store_dwordx4 v193, v[134:137], s[88:89] offset:256
	v_add_u32_e32 v193, 0x8000, v193
	global_load_dwordx4 v[146:149], v0, s[22:23]
	global_load_dwordx4 v[150:153], v0, s[22:23] offset:256
	v_add_u32_e32 v0, 0x18000, v0
	global_load_dwordx4 v[154:157], v0, s[22:23]
	global_load_dwordx4 v[158:161], v0, s[22:23] offset:256
	v_add_u32_e32 v0, 0x78000, v0
	s_waitcnt vmcnt(6)
	v_lshlrev_b32_e32 v184, 16, v138
	v_lshlrev_b32_e32 v185, 16, v139
	v_lshlrev_b32_e32 v186, 16, v140
	v_lshlrev_b32_e32 v187, 16, v141
	v_and_b32_e32 v138, 0xffff0000, v138
	v_and_b32_e32 v139, 0xffff0000, v139
	v_and_b32_e32 v140, 0xffff0000, v140
	v_and_b32_e32 v141, 0xffff0000, v141
	v_mul_f32_e32 v110, v110, v184
	v_mul_f32_e32 v111, v111, v138
	v_mul_f32_e32 v112, v112, v185
	v_mul_f32_e32 v113, v113, v139
	v_mul_f32_e32 v106, v106, v186
	v_mul_f32_e32 v107, v107, v140
	v_mul_f32_e32 v108, v108, v187
	v_mul_f32_e32 v109, v109, v141
	v_cvt_pk_bf16_f32 v138, v110, v111
	v_cvt_pk_bf16_f32 v139, v112, v113
	v_cvt_pk_bf16_f32 v140, v106, v107
	v_cvt_pk_bf16_f32 v141, v108, v109
	v_lshlrev_b32_e32 v184, 16, v142
	v_lshlrev_b32_e32 v185, 16, v143
	v_lshlrev_b32_e32 v186, 16, v144
	v_lshlrev_b32_e32 v187, 16, v145
	v_and_b32_e32 v142, 0xffff0000, v142
	v_and_b32_e32 v143, 0xffff0000, v143
	v_and_b32_e32 v144, 0xffff0000, v144
	v_and_b32_e32 v145, 0xffff0000, v145
	v_mul_f32_e32 v102, v102, v184
	v_mul_f32_e32 v103, v103, v142
	v_mul_f32_e32 v104, v104, v185
	v_mul_f32_e32 v105, v105, v143
	v_mul_f32_e32 v98, v98, v186
	v_mul_f32_e32 v99, v99, v144
	v_mul_f32_e32 v100, v100, v187
	v_mul_f32_e32 v101, v101, v145
	v_cvt_pk_bf16_f32 v142, v102, v103
	v_cvt_pk_bf16_f32 v143, v104, v105
	v_cvt_pk_bf16_f32 v144, v98, v99
	v_cvt_pk_bf16_f32 v145, v100, v101
	global_store_dwordx4 v193, v[138:141], s[88:89]
	global_store_dwordx4 v193, v[142:145], s[88:89] offset:256
	v_add_u32_e32 v193, 0x8000, v193
	global_load_dwordx4 v[162:165], v0, s[22:23]
	global_load_dwordx4 v[126:129], v0, s[22:23] offset:256
	v_add_u32_e32 v0, 0x18000, v0
	s_waitcnt vmcnt(6)
; __device__ __forceinline__ f32x4 unpk4(u32x2 p) { f32x4 r; r[0] = __uint_as_float(p.x << 16); r[1] = __uint_as_float(p.x & 0xffff0000u); r[2] = __uint_as_float(p.y << 16); r[3] = __uint_as_float(p.y & 0xffff0000u); return r; }
; __device__ __forceinline__ u32x4 pk8(f32x4 a, f32x4 b) { const u32x2 p = pk4(a), q = pk4(b); return (u32x4){p.x, p.y, q.x, q.y}; }
; template <int K>
; __device__ __forceinline__ void epilogue_p(const f32x4 (&acc)[2][2][4][2], const Unit& u, const EpiDesc& E, const Ctx& C, int wr, int wc, int fr, int fq) {
;     ...
;                     const int row = row0 + 128 * ai + 16 * (2 * mh + m2), col = 256 * u.pn + 128 * bj + lc8;
;                     gq[m2][bj] = *(const u32x4*)(C.G + (size_t)row * 3072 + seg * 1024 + col);
;                     if (seg > 0) mf[m2][bj] = *(const u32x4*)(C.MIXB + (size_t)row * DM + col); else mf[m2][bj] = (u32x4){0u, 0u, 0u, 0u};
;                 }
; #pragma unroll
;             for (int m2 = 0; m2 < 2; ++m2)
; #pragma unroll
;                 for (int bj = 0; bj < 2; ++bj) {
;                     const int m = 2 * mh + m2;
;                     const int row = row0 + 128 * ai + 16 * m, col = 256 * u.pn + 128 * bj + lc8;
;                     const f32x4 r0 = acc[ai][bj][m][0] * unpk4((u32x2){gq[m2][bj].x, gq[m2][bj].y}) + unpk4((u32x2){mf[m2][bj].x, mf[m2][bj].y});
;                     const f32x4 r1 = acc[ai][bj][m][1] * unpk4((u32x2){gq[m2][bj].z, gq[m2][bj].w}) + unpk4((u32x2){mf[m2][bj].z, mf[m2][bj].w});
;                     *(u32x4*)(C.MIXB + (size_t)row * DM + col) = pk8(r0, r1);
;                 }
	v_lshlrev_b32_e32 v184, 16, v146
	v_lshlrev_b32_e32 v185, 16, v147
	v_lshlrev_b32_e32 v186, 16, v148
	v_lshlrev_b32_e32 v187, 16, v149
	v_and_b32_e32 v146, 0xffff0000, v146
	v_and_b32_e32 v147, 0xffff0000, v147
	v_and_b32_e32 v148, 0xffff0000, v148
	v_and_b32_e32 v149, 0xffff0000, v149
	v_mul_f32_e32 v94, v94, v184
	v_mul_f32_e32 v95, v95, v146
	v_mul_f32_e32 v96, v96, v185
	v_mul_f32_e32 v97, v97, v147
	v_mul_f32_e32 v90, v90, v186
	v_mul_f32_e32 v91, v91, v148
	v_mul_f32_e32 v92, v92, v187
	v_mul_f32_e32 v93, v93, v149
	v_cvt_pk_bf16_f32 v146, v94, v95
	v_cvt_pk_bf16_f32 v147, v96, v97
	v_cvt_pk_bf16_f32 v148, v90, v91
	v_cvt_pk_bf16_f32 v149, v92, v93
	v_lshlrev_b32_e32 v184, 16, v150
	v_lshlrev_b32_e32 v185, 16, v151
	v_lshlrev_b32_e32 v186, 16, v152
	v_lshlrev_b32_e32 v187, 16, v153
	v_and_b32_e32 v150, 0xffff0000, v150
	v_and_b32_e32 v151, 0xffff0000, v151
	v_and_b32_e32 v152, 0xffff0000, v152
	v_and_b32_e32 v153, 0xffff0000, v153
	v_mul_f32_e32 v86, v86, v184
	v_mul_f32_e32 v87, v87, v150
	v_mul_f32_e32 v88, v88, v185
	v_mul_f32_e32 v89, v89, v151
	v_mul_f32_e32 v82, v82, v186
	v_mul_f32_e32 v83, v83, v152
	v_mul_f32_e32 v84, v84, v187
	v_mul_f32_e32 v85, v85, v153
	v_cvt_pk_bf16_f32 v150, v86, v87
	v_cvt_pk_bf16_f32 v151, v88, v89
	v_cvt_pk_bf16_f32 v152, v82, v83
	v_cvt_pk_bf16_f32 v153, v84, v85
	global_store_dwordx4 v193, v[146:149], s[88:89]
	global_store_dwordx4 v193, v[150:153], s[88:89] offset:256
	v_add_u32_e32 v193, 0x8000, v193
	global_load_dwordx4 v[122:125], v0, s[22:23]
	global_load_dwordx4 v[118:121], v0, s[22:23] offset:256
	v_add_u32_e32 v0, 0x18000, v0
	s_waitcnt vmcnt(8)
	v_lshlrev_b32_e32 v184, 16, v154
	v_lshlrev_b32_e32 v185, 16, v155
	v_lshlrev_b32_e32 v186, 16, v156
	v_lshlrev_b32_e32 v187, 16, v157
	v_and_b32_e32 v154, 0xffff0000, v154
	v_and_b32_e32 v155, 0xffff0000, v155
	v_and_b32_e32 v156, 0xffff0000, v156
	v_and_b32_e32 v157, 0xffff0000, v157
	v_mul_f32_e32 v78, v78, v184
	v_mul_f32_e32 v79, v79, v154
	v_mul_f32_e32 v80, v80, v185
	v_mul_f32_e32 v81, v81, v155
	v_mul_f32_e32 v74, v74, v186
	v_mul_f32_e32 v75, v75, v156
	v_mul_f32_e32 v76, v76, v187
	v_mul_f32_e32 v77, v77, v157
	v_cvt_pk_bf16_f32 v154, v78, v79
	v_cvt_pk_bf16_f32 v155, v80, v81
	v_cvt_pk_bf16_f32 v156, v74, v75
	v_cvt_pk_bf16_f32 v157, v76, v77
	v_lshlrev_b32_e32 v184, 16, v158
	v_lshlrev_b32_e32 v185, 16, v159
	v_lshlrev_b32_e32 v186, 16, v160
	v_lshlrev_b32_e32 v187, 16, v161
	v_and_b32_e32 v158, 0xffff0000, v158
	v_and_b32_e32 v159, 0xffff0000, v159
	v_and_b32_e32 v160, 0xffff0000, v160
	v_and_b32_e32 v161, 0xffff0000, v161
	v_mul_f32_e32 v70, v70, v184
	v_mul_f32_e32 v71, v71, v158
	v_mul_f32_e32 v72, v72, v185
	v_mul_f32_e32 v73, v73, v159
	v_mul_f32_e32 v66, v66, v186
	v_mul_f32_e32 v67, v67, v160
	v_mul_f32_e32 v68, v68, v187
	v_mul_f32_e32 v69, v69, v161
	v_cvt_pk_bf16_f32 v158, v70, v71
	v_cvt_pk_bf16_f32 v159, v72, v73
	v_cvt_pk_bf16_f32 v160, v66, v67
	v_cvt_pk_bf16_f32 v161, v68, v69
	global_store_dwordx4 v193, v[154:157], s[88:89]
	global_store_dwordx4 v193, v[158:161], s[88:89] offset:256
	v_add_u32_e32 v193, 0x28000, v193
	global_load_dwordx4 v[114:117], v0, s[22:23]
	global_load_dwordx4 v[110:113], v0, s[22:23] offset:256
	v_add_u32_e32 v0, 0x18000, v0
	s_waitcnt vmcnt(8)
	v_lshlrev_b32_e32 v184, 16, v162
	v_lshlrev_b32_e32 v185, 16, v163
	v_lshlrev_b32_e32 v186, 16, v164
	v_lshlrev_b32_e32 v187, 16, v165
	v_and_b32_e32 v162, 0xffff0000, v162
	v_and_b32_e32 v163, 0xffff0000, v163
	v_and_b32_e32 v164, 0xffff0000, v164
	v_and_b32_e32 v165, 0xffff0000, v165
	v_mul_f32_e32 v62, v62, v184
	v_mul_f32_e32 v63, v63, v162
	v_mul_f32_e32 v64, v64, v185
	v_mul_f32_e32 v65, v65, v163
	v_mul_f32_e32 v58, v58, v186
	v_mul_f32_e32 v59, v59, v164
	v_mul_f32_e32 v60, v60, v187
	v_mul_f32_e32 v61, v61, v165
	v_cvt_pk_bf16_f32 v162, v62, v63
	v_cvt_pk_bf16_f32 v163, v64, v65
	v_cvt_pk_bf16_f32 v164, v58, v59
	v_cvt_pk_bf16_f32 v165, v60, v61
	v_lshlrev_b32_e32 v184, 16, v126
	v_lshlrev_b32_e32 v185, 16, v127
	v_lshlrev_b32_e32 v186, 16, v128
	v_lshlrev_b32_e32 v187, 16, v129
	v_and_b32_e32 v126, 0xffff0000, v126
	v_and_b32_e32 v127, 0xffff0000, v127
	v_and_b32_e32 v128, 0xffff0000, v128
	v_and_b32_e32 v129, 0xffff0000, v129
	v_mul_f32_e32 v54, v54, v184
	v_mul_f32_e32 v55, v55, v126
	v_mul_f32_e32 v56, v56, v185
	v_mul_f32_e32 v57, v57, v127
	v_mul_f32_e32 v50, v50, v186
	v_mul_f32_e32 v51, v51, v128
	v_mul_f32_e32 v52, v52, v187
	v_mul_f32_e32 v53, v53, v129
	v_cvt_pk_bf16_f32 v126, v54, v55
	v_cvt_pk_bf16_f32 v127, v56, v57
	v_cvt_pk_bf16_f32 v128, v50, v51
	v_cvt_pk_bf16_f32 v129, v52, v53
	global_store_dwordx4 v193, v[162:165], s[88:89]
	global_store_dwordx4 v193, v[126:129], s[88:89] offset:256
	v_add_u32_e32 v193, 0x8000, v193
	global_load_dwordx4 v[106:109], v0, s[22:23]
	global_load_dwordx4 v[102:105], v0, s[22:23] offset:256
	s_waitcnt vmcnt(8)
; __device__ __forceinline__ f32x4 unpk4(u32x2 p) { f32x4 r; r[0] = __uint_as_float(p.x << 16); r[1] = __uint_as_float(p.x & 0xffff0000u); r[2] = __uint_as_float(p.y << 16); r[3] = __uint_as_float(p.y & 0xffff0000u); return r; }
; __device__ __forceinline__ u32x4 pk8(f32x4 a, f32x4 b) { const u32x2 p = pk4(a), q = pk4(b); return (u32x4){p.x, p.y, q.x, q.y}; }
; template <int K>
; __device__ __forceinline__ void epilogue_p(const f32x4 (&acc)[2][2][4][2], const Unit& u, const EpiDesc& E, const Ctx& C, int wr, int wc, int fr, int fq) {
;     ...
;                     const int row = row0 + 128 * ai + 16 * (2 * mh + m2), col = 256 * u.pn + 128 * bj + lc8;
;                     gq[m2][bj] = *(const u32x4*)(C.G + (size_t)row * 3072 + seg * 1024 + col);
;                     if (seg > 0) mf[m2][bj] = *(const u32x4*)(C.MIXB + (size_t)row * DM + col); else mf[m2][bj] = (u32x4){0u, 0u, 0u, 0u};
;                 }
; #pragma unroll
;             for (int m2 = 0; m2 < 2; ++m2)
; #pragma unroll
;                 for (int bj = 0; bj < 2; ++bj) {
;                     const int m = 2 * mh + m2;
;                     const int row = row0 + 128 * ai + 16 * m, col = 256 * u.pn + 128 * bj + lc8;
;                     const f32x4 r0 = acc[ai][bj][m][0] * unpk4((u32x2){gq[m2][bj].x, gq[m2][bj].y}) + unpk4((u32x2){mf[m2][bj].x, mf[m2][bj].y});
;                     const f32x4 r1 = acc[ai][bj][m][1] * unpk4((u32x2){gq[m2][bj].z, gq[m2][bj].w}) + unpk4((u32x2){mf[m2][bj].z, mf[m2][bj].w});
;                     *(u32x4*)(C.MIXB + (size_t)row * DM + col) = pk8(r0, r1);
;                 }
	v_lshlrev_b32_e32 v184, 16, v122
	v_lshlrev_b32_e32 v185, 16, v123
	v_lshlrev_b32_e32 v186, 16, v124
	v_lshlrev_b32_e32 v187, 16, v125
	v_and_b32_e32 v122, 0xffff0000, v122
	v_and_b32_e32 v123, 0xffff0000, v123
	v_and_b32_e32 v124, 0xffff0000, v124
	v_and_b32_e32 v125, 0xffff0000, v125
	v_mul_f32_e32 v46, v46, v184
	v_mul_f32_e32 v47, v47, v122
	v_mul_f32_e32 v48, v48, v185
	v_mul_f32_e32 v49, v49, v123
	v_mul_f32_e32 v42, v42, v186
	v_mul_f32_e32 v43, v43, v124
	v_mul_f32_e32 v44, v44, v187
	v_mul_f32_e32 v45, v45, v125
	v_cvt_pk_bf16_f32 v122, v46, v47
	v_cvt_pk_bf16_f32 v123, v48, v49
	v_cvt_pk_bf16_f32 v124, v42, v43
	v_cvt_pk_bf16_f32 v125, v44, v45
	v_lshlrev_b32_e32 v184, 16, v118
	v_lshlrev_b32_e32 v185, 16, v119
	v_lshlrev_b32_e32 v186, 16, v120
	v_lshlrev_b32_e32 v187, 16, v121
	v_and_b32_e32 v118, 0xffff0000, v118
	v_and_b32_e32 v119, 0xffff0000, v119
	v_and_b32_e32 v120, 0xffff0000, v120
	v_and_b32_e32 v121, 0xffff0000, v121
	v_mul_f32_e32 v38, v38, v184
	v_mul_f32_e32 v39, v39, v118
	v_mul_f32_e32 v40, v40, v185
	v_mul_f32_e32 v41, v41, v119
	v_mul_f32_e32 v34, v34, v186
	v_mul_f32_e32 v35, v35, v120
	v_mul_f32_e32 v36, v36, v187
	v_mul_f32_e32 v37, v37, v121
	v_cvt_pk_bf16_f32 v118, v38, v39
	v_cvt_pk_bf16_f32 v119, v40, v41
	v_cvt_pk_bf16_f32 v120, v34, v35
	v_cvt_pk_bf16_f32 v121, v36, v37
	global_store_dwordx4 v193, v[122:125], s[88:89]
	global_store_dwordx4 v193, v[118:121], s[88:89] offset:256
	v_add_u32_e32 v193, 0x8000, v193
	s_waitcnt vmcnt(6)
	v_lshlrev_b32_e32 v184, 16, v114
	v_lshlrev_b32_e32 v185, 16, v115
	v_lshlrev_b32_e32 v186, 16, v116
	v_lshlrev_b32_e32 v187, 16, v117
	v_and_b32_e32 v114, 0xffff0000, v114
	v_and_b32_e32 v115, 0xffff0000, v115
	v_and_b32_e32 v116, 0xffff0000, v116
	v_and_b32_e32 v117, 0xffff0000, v117
	v_mul_f32_e32 v30, v30, v184
	v_mul_f32_e32 v31, v31, v114
	v_mul_f32_e32 v32, v32, v185
	v_mul_f32_e32 v33, v33, v115
	v_mul_f32_e32 v26, v26, v186
	v_mul_f32_e32 v27, v27, v116
	v_mul_f32_e32 v28, v28, v187
	v_mul_f32_e32 v29, v29, v117
	v_cvt_pk_bf16_f32 v114, v30, v31
	v_cvt_pk_bf16_f32 v115, v32, v33
	v_cvt_pk_bf16_f32 v116, v26, v27
	v_cvt_pk_bf16_f32 v117, v28, v29
	v_lshlrev_b32_e32 v184, 16, v110
	v_lshlrev_b32_e32 v185, 16, v111
	v_lshlrev_b32_e32 v186, 16, v112
	v_lshlrev_b32_e32 v187, 16, v113
	v_and_b32_e32 v110, 0xffff0000, v110
	v_and_b32_e32 v111, 0xffff0000, v111
	v_and_b32_e32 v112, 0xffff0000, v112
	v_and_b32_e32 v113, 0xffff0000, v113
	v_mul_f32_e32 v22, v22, v184
	v_mul_f32_e32 v23, v23, v110
	v_mul_f32_e32 v24, v24, v185
	v_mul_f32_e32 v25, v25, v111
	v_mul_f32_e32 v18, v18, v186
	v_mul_f32_e32 v19, v19, v112
	v_mul_f32_e32 v20, v20, v187
	v_mul_f32_e32 v21, v21, v113
	v_cvt_pk_bf16_f32 v110, v22, v23
	v_cvt_pk_bf16_f32 v111, v24, v25
	v_cvt_pk_bf16_f32 v112, v18, v19
	v_cvt_pk_bf16_f32 v113, v20, v21
	global_store_dwordx4 v193, v[114:117], s[88:89]
	global_store_dwordx4 v193, v[110:113], s[88:89] offset:256
	v_add_u32_e32 v193, 0x8000, v193
	s_waitcnt vmcnt(4)
	v_lshlrev_b32_e32 v184, 16, v106
	v_lshlrev_b32_e32 v185, 16, v107
	v_lshlrev_b32_e32 v186, 16, v108
	v_lshlrev_b32_e32 v187, 16, v109
	v_and_b32_e32 v106, 0xffff0000, v106
	v_and_b32_e32 v107, 0xffff0000, v107
	v_and_b32_e32 v108, 0xffff0000, v108
	v_and_b32_e32 v109, 0xffff0000, v109
	v_mul_f32_e32 v14, v14, v184
	v_mul_f32_e32 v15, v15, v106
	v_mul_f32_e32 v16, v16, v185
	v_mul_f32_e32 v17, v17, v107
	v_mul_f32_e32 v10, v10, v186
	v_mul_f32_e32 v11, v11, v108
	v_mul_f32_e32 v12, v12, v187
	v_mul_f32_e32 v13, v13, v109
	v_cvt_pk_bf16_f32 v106, v14, v15
	v_cvt_pk_bf16_f32 v107, v16, v17
	v_cvt_pk_bf16_f32 v108, v10, v11
	v_cvt_pk_bf16_f32 v109, v12, v13
	v_lshlrev_b32_e32 v184, 16, v102
	v_lshlrev_b32_e32 v185, 16, v103
	v_lshlrev_b32_e32 v186, 16, v104
	v_lshlrev_b32_e32 v187, 16, v105
	v_and_b32_e32 v102, 0xffff0000, v102
	v_and_b32_e32 v103, 0xffff0000, v103
	v_and_b32_e32 v104, 0xffff0000, v104
	v_and_b32_e32 v105, 0xffff0000, v105
	v_mul_f32_e32 v6, v6, v184
	v_mul_f32_e32 v7, v7, v102
	v_mul_f32_e32 v8, v8, v185
	v_mul_f32_e32 v9, v9, v103
	v_mul_f32_e32 v2, v2, v186
	v_mul_f32_e32 v3, v3, v104
	v_mul_f32_e32 v4, v4, v187
	v_mul_f32_e32 v5, v5, v105
	v_cvt_pk_bf16_f32 v102, v6, v7
	v_cvt_pk_bf16_f32 v103, v8, v9
	v_cvt_pk_bf16_f32 v104, v2, v3
	v_cvt_pk_bf16_f32 v105, v4, v5
	global_store_dwordx4 v193, v[106:109], s[88:89]
	global_store_dwordx4 v193, v[102:105], s[88:89] offset:256
	s_branch .LBB0_213
